# Strategy 9 (7.11): rotated the K-loop back edge of the rstd-scaled GEMM instance - counter update, exit test and next-iteration address setup moved in front of the closing barrier
# baseline (speedup 1.0000x reference)
; #define PG8_STAGE(bufoff, gbase, voff) do { _Pragma("unroll") for (int _i = 0; _i < 2; ++_i) \
;         __builtin_amdgcn_global_load_lds((const unsigned*)((const char*)(gbase) + (voff)[_i]), (PG8_LAS unsigned*)(lds + (bufoff) + ldsw + _i * 8192), 16, 0, 0); } while (0)
; #define PG8_LDA(dst, b, h) do { _Pragma("unroll") for (int m = 0; m < 4; ++m) _Pragma("unroll") for (int k = 0; k < 2; ++k) dst[m][k] = *(const PG8_LAS bf16x8*)(lds + PG8_SA(b, h) + aoff + m * 2048 + k * 1024); } while (0)
; #define PG8_LDB(dst, b, h) do { _Pragma("unroll") for (int n = 0; n < 2; ++n) _Pragma("unroll") for (int k = 0; k < 2; ++k) dst[n][k] = *(const PG8_LAS bf16x8*)(lds + PG8_SB(b, h) + boff + n * 2048 + k * 1024); } while (0)
; #define PG8_MMA(ai, bj, At, Bt) do { __builtin_amdgcn_s_setprio(1); _Pragma("unroll") for (int m = 0; m < 4; ++m) _Pragma("unroll") for (int n = 0; n < 2; ++n) _Pragma("unroll") for (int k = 0; k < 2; ++k) \
;         acc[ai][bj][m][n] = __builtin_amdgcn_mfma_f32_16x16x32_bf16(Bt[n][k], At[m][k], acc[ai][bj][m][n], 0, 0, 0); __builtin_amdgcn_s_setprio(0); } while (0)
; #define PG8_WAIT_V(n) asm volatile("s_waitcnt vmcnt(" #n ")" ::: "memory")
; #define PG8_WAIT_L(n) asm volatile("s_waitcnt lgkmcnt(" #n ")" ::: "memory")
; #define PG8_BAR __builtin_amdgcn_s_barrier()
; #define PG8_SCHED __builtin_amdgcn_sched_barrier(0)
; template <class Epi, class Sched, bool ALIGN_EPI = false, bool SP2 = false>
; __device__ __forceinline__ void gemm_phase(PG8_LAS unsigned char* lds, const Gemm g, const Sched& S, const Epi& E) {
;     ...
;             if constexpr (SP2) {
;             PG8_LDB(B0, 0, 0); PG8_LDB(B1, 0, 1); PG8_SCHED; PG8_LDA(At, 0, 0); PG8_STAGE(PG8_SA(1, 1), a1 + hstep, voffA);
;             PG8_WAIT_V(8); PG8_WAIT_L(0); PG8_BAR; PG8_MMA(0, 0, At, B0); PG8_MMA(0, 1, At, B1); PG8_BAR; PG8_SCHED;
;             PG8_LDA(At, 0, 1); PG8_STAGE(PG8_SB(0, 0), b2, voffB); PG8_STAGE(PG8_SB(0, 1), b2 + hstep, voffB); PG8_STAGE(PG8_SA(0, 0), a2, voffA);
;             PG8_WAIT_V(8); PG8_WAIT_L(0); PG8_BAR; PG8_MMA(1, 0, At, B0); PG8_MMA(1, 1, At, B1); PG8_BAR; PG8_SCHED;
.Lks_head:
	ds_read_b128 v[56:59], v116
	ds_read_b128 v[76:79], v116 offset:1024
	ds_read_b128 v[96:99], v116 offset:2048
	ds_read_b128 v[116:119], v116 offset:3072
	ds_read_b128 v[136:139], v176
	ds_read_b128 v[148:151], v176 offset:1024
	ds_read_b128 v[152:155], v176 offset:2048
	ds_read_b128 v[176:179], v176 offset:3072
	v_lshl_add_u64 v[234:235], s[44:45], 0, v[172:173]
	s_add_i32 m0, s11, 0xc000
	ds_read_b128 v[180:183], v217
	ds_read_b128 v[184:187], v217 offset:1024
	ds_read_b128 v[188:191], v217 offset:2048
	ds_read_b128 v[192:195], v217 offset:3072
	ds_read_b128 v[218:221], v217 offset:4096
	ds_read_b128 v[222:225], v217 offset:5120
	ds_read_b128 v[226:229], v217 offset:6144
	ds_read_b128 v[230:233], v217 offset:7168
	global_load_lds_dwordx4 v[234:235], off
	v_lshl_add_u64 v[234:235], s[44:45], 0, v[174:175]
	s_add_i32 m0, s11, 0xe000
	s_nop 0
	global_load_lds_dwordx4 v[234:235], off
	s_waitcnt vmcnt(8)
	s_waitcnt lgkmcnt(0)
	s_barrier
	s_setprio 1
	s_waitcnt lgkmcnt(0)
	v_mfma_f32_16x16x32_bf16 v[144:147], v[56:59], v[180:183], v[144:147]
	v_mfma_f32_16x16x32_bf16 v[140:143], v[96:99], v[180:183], v[140:143]
	v_mfma_f32_16x16x32_bf16 v[124:127], v[56:59], v[188:191], v[124:127]
	v_mfma_f32_16x16x32_bf16 v[120:123], v[96:99], v[188:191], v[120:123]
	v_mfma_f32_16x16x32_bf16 v[104:107], v[56:59], v[218:221], v[104:107]
	v_mfma_f32_16x16x32_bf16 v[100:103], v[96:99], v[218:221], v[100:103]
	v_mfma_f32_16x16x32_bf16 v[84:87], v[56:59], v[226:229], v[84:87]
	v_mfma_f32_16x16x32_bf16 v[80:83], v[96:99], v[226:229], v[80:83]
	v_mfma_f32_16x16x32_bf16 v[144:147], v[76:79], v[184:187], v[144:147]
	v_mfma_f32_16x16x32_bf16 v[140:143], v[116:119], v[184:187], v[140:143]
	v_mfma_f32_16x16x32_bf16 v[124:127], v[76:79], v[192:195], v[124:127]
	v_mfma_f32_16x16x32_bf16 v[120:123], v[116:119], v[192:195], v[120:123]
	v_mfma_f32_16x16x32_bf16 v[104:107], v[76:79], v[222:225], v[104:107]
	v_mfma_f32_16x16x32_bf16 v[100:103], v[116:119], v[222:225], v[100:103]
	v_mfma_f32_16x16x32_bf16 v[84:87], v[76:79], v[230:233], v[84:87]
	v_mfma_f32_16x16x32_bf16 v[80:83], v[116:119], v[230:233], v[80:83]
	s_setprio 0
	s_setprio 1
	v_mfma_f32_16x16x32_bf16 v[132:135], v[136:139], v[180:183], v[132:135]
	v_mfma_f32_16x16x32_bf16 v[128:131], v[152:155], v[180:183], v[128:131]
	v_mfma_f32_16x16x32_bf16 v[112:115], v[136:139], v[188:191], v[112:115]
	v_mfma_f32_16x16x32_bf16 v[108:111], v[152:155], v[188:191], v[108:111]
	v_mfma_f32_16x16x32_bf16 v[92:95], v[136:139], v[218:221], v[92:95]
	v_mfma_f32_16x16x32_bf16 v[88:91], v[152:155], v[218:221], v[88:91]
	v_mfma_f32_16x16x32_bf16 v[72:75], v[136:139], v[226:229], v[72:75]
	v_mfma_f32_16x16x32_bf16 v[68:71], v[152:155], v[226:229], v[68:71]
	v_mfma_f32_16x16x32_bf16 v[132:135], v[148:151], v[184:187], v[132:135]
	v_mfma_f32_16x16x32_bf16 v[128:131], v[176:179], v[184:187], v[128:131]
	v_mfma_f32_16x16x32_bf16 v[112:115], v[148:151], v[192:195], v[112:115]
	v_mfma_f32_16x16x32_bf16 v[108:111], v[176:179], v[192:195], v[108:111]
	v_mfma_f32_16x16x32_bf16 v[92:95], v[148:151], v[222:225], v[92:95]
	v_mfma_f32_16x16x32_bf16 v[88:91], v[176:179], v[222:225], v[88:91]
	v_mfma_f32_16x16x32_bf16 v[72:75], v[148:151], v[230:233], v[72:75]
	v_mfma_f32_16x16x32_bf16 v[68:71], v[176:179], v[230:233], v[68:71]
	s_setprio 0
	s_barrier
	s_add_i32 s56, s57, s10
	v_lshl_add_u64 v[234:235], s[74:75], 0, v[156:157]
	s_mov_b32 m0, s56
	ds_read_b128 v[180:183], v217 offset:16384
	ds_read_b128 v[184:187], v217 offset:17408
	ds_read_b128 v[188:191], v217 offset:18432
	ds_read_b128 v[192:195], v217 offset:19456
	ds_read_b128 v[218:221], v217 offset:20480
	ds_read_b128 v[222:225], v217 offset:21504
	ds_read_b128 v[226:229], v217 offset:22528
	ds_read_b128 v[230:233], v217 offset:23552
	global_load_lds_dwordx4 v[234:235], off
	s_add_i32 m0, s56, 0x2000
	s_add_u32 s56, s74, 0x40000
	v_lshl_add_u64 v[236:237], s[74:75], 0, v[168:169]
	s_addc_u32 s57, s75, 0
	s_add_i32 s55, s55, s10
	global_load_lds_dwordx4 v[236:237], off
	v_lshl_add_u64 v[238:239], s[56:57], 0, v[156:157]
	s_mov_b32 m0, s55
	v_lshl_add_u64 v[240:241], s[76:77], 0, v[166:167]
	global_load_lds_dwordx4 v[238:239], off
	v_lshl_add_u64 v[238:239], s[56:57], 0, v[168:169]
	s_add_i32 m0, s55, 0x2000
	s_nop 0
	global_load_lds_dwordx4 v[238:239], off
	v_lshl_add_u64 v[238:239], s[76:77], 0, v[164:165]
	s_mov_b32 m0, s11
	s_nop 0
	global_load_lds_dwordx4 v[238:239], off
	s_mov_b32 m0, s12
	s_nop 0
	global_load_lds_dwordx4 v[240:241], off
	s_waitcnt vmcnt(8)
	s_waitcnt lgkmcnt(0)
	s_barrier
; #define PG8_STAGE(bufoff, gbase, voff) do { _Pragma("unroll") for (int _i = 0; _i < 2; ++_i) \
;         __builtin_amdgcn_global_load_lds((const unsigned*)((const char*)(gbase) + (voff)[_i]), (PG8_LAS unsigned*)(lds + (bufoff) + ldsw + _i * 8192), 16, 0, 0); } while (0)
; #define PG8_LDA(dst, b, h) do { _Pragma("unroll") for (int m = 0; m < 4; ++m) _Pragma("unroll") for (int k = 0; k < 2; ++k) dst[m][k] = *(const PG8_LAS bf16x8*)(lds + PG8_SA(b, h) + aoff + m * 2048 + k * 1024); } while (0)
; #define PG8_LDB(dst, b, h) do { _Pragma("unroll") for (int n = 0; n < 2; ++n) _Pragma("unroll") for (int k = 0; k < 2; ++k) dst[n][k] = *(const PG8_LAS bf16x8*)(lds + PG8_SB(b, h) + boff + n * 2048 + k * 1024); } while (0)
; #define PG8_MMA(ai, bj, At, Bt) do { __builtin_amdgcn_s_setprio(1); _Pragma("unroll") for (int m = 0; m < 4; ++m) _Pragma("unroll") for (int n = 0; n < 2; ++n) _Pragma("unroll") for (int k = 0; k < 2; ++k) \
;         acc[ai][bj][m][n] = __builtin_amdgcn_mfma_f32_16x16x32_bf16(Bt[n][k], At[m][k], acc[ai][bj][m][n], 0, 0, 0); __builtin_amdgcn_s_setprio(0); } while (0)
; #define PG8_WAIT_V(n) asm volatile("s_waitcnt vmcnt(" #n ")" ::: "memory")
; #define PG8_WAIT_L(n) asm volatile("s_waitcnt lgkmcnt(" #n ")" ::: "memory")
; #define PG8_BAR __builtin_amdgcn_s_barrier()
; #define PG8_SCHED __builtin_amdgcn_sched_barrier(0)
; template <class Epi, class Sched, bool ALIGN_EPI = false, bool SP2 = false>
; __device__ __forceinline__ void gemm_phase(PG8_LAS unsigned char* lds, const Gemm g, const Sched& S, const Epi& E) {
;     ...
;             PG8_WAIT_V(8); PG8_WAIT_L(0); PG8_BAR; PG8_MMA(1, 0, At, B0); PG8_MMA(1, 1, At, B1); PG8_BAR; PG8_SCHED;
;             PG8_LDB(B0, 1, 0); PG8_LDB(B1, 1, 1); PG8_SCHED; PG8_LDA(At, 1, 0); PG8_STAGE(PG8_SA(0, 1), a2 + hstep, voffA);
;             PG8_WAIT_V(8); PG8_WAIT_L(0); PG8_BAR; PG8_MMA(0, 0, At, B0); PG8_MMA(0, 1, At, B1); PG8_BAR; PG8_SCHED;
;             PG8_LDA(At, 1, 1); PG8_STAGE(PG8_SB(1, 0), b3, voffB); PG8_STAGE(PG8_SB(1, 1), b3 + hstep, voffB); PG8_STAGE(PG8_SA(1, 0), a3, voffA);
	s_setprio 1
	s_waitcnt lgkmcnt(0)
	v_mfma_f32_16x16x32_bf16 v[64:67], v[56:59], v[180:183], v[64:67]
	v_mfma_f32_16x16x32_bf16 v[60:63], v[96:99], v[180:183], v[60:63]
	v_mfma_f32_16x16x32_bf16 v[44:47], v[56:59], v[188:191], v[44:47]
	v_mfma_f32_16x16x32_bf16 v[40:43], v[96:99], v[188:191], v[40:43]
	v_mfma_f32_16x16x32_bf16 v[28:31], v[56:59], v[218:221], v[28:31]
	v_mfma_f32_16x16x32_bf16 v[24:27], v[96:99], v[218:221], v[24:27]
	v_mfma_f32_16x16x32_bf16 v[12:15], v[56:59], v[226:229], v[12:15]
	v_mfma_f32_16x16x32_bf16 v[8:11], v[96:99], v[226:229], v[8:11]
	v_mfma_f32_16x16x32_bf16 v[64:67], v[76:79], v[184:187], v[64:67]
	v_mfma_f32_16x16x32_bf16 v[60:63], v[116:119], v[184:187], v[60:63]
	v_mfma_f32_16x16x32_bf16 v[44:47], v[76:79], v[192:195], v[44:47]
	v_mfma_f32_16x16x32_bf16 v[40:43], v[116:119], v[192:195], v[40:43]
	v_mfma_f32_16x16x32_bf16 v[28:31], v[76:79], v[222:225], v[28:31]
	v_mfma_f32_16x16x32_bf16 v[24:27], v[116:119], v[222:225], v[24:27]
	v_mfma_f32_16x16x32_bf16 v[12:15], v[76:79], v[230:233], v[12:15]
	v_mfma_f32_16x16x32_bf16 v[8:11], v[116:119], v[230:233], v[8:11]
	s_setprio 0
	s_setprio 1
	v_mfma_f32_16x16x32_bf16 v[52:55], v[136:139], v[180:183], v[52:55]
	v_mfma_f32_16x16x32_bf16 v[48:51], v[152:155], v[180:183], v[48:51]
	v_mfma_f32_16x16x32_bf16 v[36:39], v[136:139], v[188:191], v[36:39]
	v_mfma_f32_16x16x32_bf16 v[32:35], v[152:155], v[188:191], v[32:35]
	v_mfma_f32_16x16x32_bf16 v[20:23], v[136:139], v[218:221], v[20:23]
	v_mfma_f32_16x16x32_bf16 v[16:19], v[152:155], v[218:221], v[16:19]
	v_mfma_f32_16x16x32_bf16 v[4:7], v[136:139], v[226:229], v[4:7]
	v_mfma_f32_16x16x32_bf16 v[0:3], v[152:155], v[226:229], v[0:3]
	v_mfma_f32_16x16x32_bf16 v[52:55], v[148:151], v[184:187], v[52:55]
	v_mfma_f32_16x16x32_bf16 v[48:51], v[176:179], v[184:187], v[48:51]
	v_mfma_f32_16x16x32_bf16 v[36:39], v[148:151], v[192:195], v[36:39]
	v_mfma_f32_16x16x32_bf16 v[32:35], v[176:179], v[192:195], v[32:35]
	v_mfma_f32_16x16x32_bf16 v[20:23], v[148:151], v[222:225], v[20:23]
	v_mfma_f32_16x16x32_bf16 v[16:19], v[176:179], v[222:225], v[16:19]
	v_mfma_f32_16x16x32_bf16 v[4:7], v[148:151], v[230:233], v[4:7]
	v_mfma_f32_16x16x32_bf16 v[0:3], v[176:179], v[230:233], v[0:3]
	s_setprio 0
	s_barrier
	s_add_i32 s55, 0, 0x18000
	s_add_i32 s58, 0, 0x1c000
	v_add_u32_e32 v116, s55, v215
	v_add_u32_e32 v176, s58, v215
	ds_read_b128 v[56:59], v116
	ds_read_b128 v[76:79], v116 offset:1024
	ds_read_b128 v[96:99], v116 offset:2048
	ds_read_b128 v[116:119], v116 offset:3072
	ds_read_b128 v[136:139], v176
	ds_read_b128 v[148:151], v176 offset:1024
	ds_read_b128 v[152:155], v176 offset:2048
	ds_read_b128 v[176:179], v176 offset:3072
	s_add_u32 s56, s76, 0x40000
	s_addc_u32 s57, s77, 0
	s_mov_b32 m0, s13
	v_lshl_add_u64 v[242:243], s[56:57], 0, v[164:165]
	ds_read_b128 v[180:183], v217 offset:32768
	ds_read_b128 v[184:187], v217 offset:33792
	ds_read_b128 v[188:191], v217 offset:34816
	ds_read_b128 v[192:195], v217 offset:35840
	ds_read_b128 v[218:221], v217 offset:36864
	ds_read_b128 v[222:225], v217 offset:37888
	ds_read_b128 v[226:229], v217 offset:38912
	ds_read_b128 v[230:233], v217 offset:39936
	global_load_lds_dwordx4 v[242:243], off
	v_lshl_add_u64 v[242:243], s[56:57], 0, v[166:167]
	s_mov_b32 m0, s14
	s_nop 0
	global_load_lds_dwordx4 v[242:243], off
	s_waitcnt vmcnt(8)
	s_waitcnt lgkmcnt(0)
	s_barrier
	s_setprio 1
	s_waitcnt lgkmcnt(0)
	v_mfma_f32_16x16x32_bf16 v[144:147], v[56:59], v[180:183], v[144:147]
	v_mfma_f32_16x16x32_bf16 v[140:143], v[96:99], v[180:183], v[140:143]
	v_mfma_f32_16x16x32_bf16 v[124:127], v[56:59], v[188:191], v[124:127]
	v_mfma_f32_16x16x32_bf16 v[120:123], v[96:99], v[188:191], v[120:123]
	v_mfma_f32_16x16x32_bf16 v[104:107], v[56:59], v[218:221], v[104:107]
	v_mfma_f32_16x16x32_bf16 v[100:103], v[96:99], v[218:221], v[100:103]
	v_mfma_f32_16x16x32_bf16 v[84:87], v[56:59], v[226:229], v[84:87]
	v_mfma_f32_16x16x32_bf16 v[80:83], v[96:99], v[226:229], v[80:83]
	v_mfma_f32_16x16x32_bf16 v[144:147], v[76:79], v[184:187], v[144:147]
	v_mfma_f32_16x16x32_bf16 v[140:143], v[116:119], v[184:187], v[140:143]
	v_mfma_f32_16x16x32_bf16 v[124:127], v[76:79], v[192:195], v[124:127]
	v_mfma_f32_16x16x32_bf16 v[120:123], v[116:119], v[192:195], v[120:123]
	v_mfma_f32_16x16x32_bf16 v[104:107], v[76:79], v[222:225], v[104:107]
	v_mfma_f32_16x16x32_bf16 v[100:103], v[116:119], v[222:225], v[100:103]
	v_mfma_f32_16x16x32_bf16 v[84:87], v[76:79], v[230:233], v[84:87]
	v_mfma_f32_16x16x32_bf16 v[80:83], v[116:119], v[230:233], v[80:83]
	s_setprio 0
	s_setprio 1
	v_mfma_f32_16x16x32_bf16 v[132:135], v[136:139], v[180:183], v[132:135]
	v_mfma_f32_16x16x32_bf16 v[128:131], v[152:155], v[180:183], v[128:131]
	v_mfma_f32_16x16x32_bf16 v[112:115], v[136:139], v[188:191], v[112:115]
	v_mfma_f32_16x16x32_bf16 v[108:111], v[152:155], v[188:191], v[108:111]
	v_mfma_f32_16x16x32_bf16 v[92:95], v[136:139], v[218:221], v[92:95]
	v_mfma_f32_16x16x32_bf16 v[88:91], v[152:155], v[218:221], v[88:91]
	v_mfma_f32_16x16x32_bf16 v[72:75], v[136:139], v[226:229], v[72:75]
	v_mfma_f32_16x16x32_bf16 v[68:71], v[152:155], v[226:229], v[68:71]
	v_mfma_f32_16x16x32_bf16 v[132:135], v[148:151], v[184:187], v[132:135]
	v_mfma_f32_16x16x32_bf16 v[128:131], v[176:179], v[184:187], v[128:131]
	v_mfma_f32_16x16x32_bf16 v[112:115], v[148:151], v[192:195], v[112:115]
	v_mfma_f32_16x16x32_bf16 v[108:111], v[176:179], v[192:195], v[108:111]
	v_mfma_f32_16x16x32_bf16 v[92:95], v[148:151], v[222:225], v[92:95]
	v_mfma_f32_16x16x32_bf16 v[88:91], v[176:179], v[222:225], v[88:91]
	v_mfma_f32_16x16x32_bf16 v[72:75], v[148:151], v[230:233], v[72:75]
	v_mfma_f32_16x16x32_bf16 v[68:71], v[176:179], v[230:233], v[68:71]
	s_setprio 0
	s_barrier
; #define PG8_STAGE(bufoff, gbase, voff) do { _Pragma("unroll") for (int _i = 0; _i < 2; ++_i) \
;         __builtin_amdgcn_global_load_lds((const unsigned*)((const char*)(gbase) + (voff)[_i]), (PG8_LAS unsigned*)(lds + (bufoff) + ldsw + _i * 8192), 16, 0, 0); } while (0)
; #define PG8_LDA(dst, b, h) do { _Pragma("unroll") for (int m = 0; m < 4; ++m) _Pragma("unroll") for (int k = 0; k < 2; ++k) dst[m][k] = *(const PG8_LAS bf16x8*)(lds + PG8_SA(b, h) + aoff + m * 2048 + k * 1024); } while (0)
; #define PG8_MMA(ai, bj, At, Bt) do { __builtin_amdgcn_s_setprio(1); _Pragma("unroll") for (int m = 0; m < 4; ++m) _Pragma("unroll") for (int n = 0; n < 2; ++n) _Pragma("unroll") for (int k = 0; k < 2; ++k) \
;         acc[ai][bj][m][n] = __builtin_amdgcn_mfma_f32_16x16x32_bf16(Bt[n][k], At[m][k], acc[ai][bj][m][n], 0, 0, 0); __builtin_amdgcn_s_setprio(0); } while (0)
; #define PG8_WAIT_V(n) asm volatile("s_waitcnt vmcnt(" #n ")" ::: "memory")
; #define PG8_WAIT_L(n) asm volatile("s_waitcnt lgkmcnt(" #n ")" ::: "memory")
; #define PG8_BAR __builtin_amdgcn_s_barrier()
; #define PG8_SCHED __builtin_amdgcn_sched_barrier(0)
; template <class Epi, class Sched, bool ALIGN_EPI = false, bool SP2 = false>
; __device__ __forceinline__ void gemm_phase(PG8_LAS unsigned char* lds, const Gemm g, const Sched& S, const Epi& E) {
;     ...
;         for (int t = 0; t < nt; t += 2) {
;             const bool last = (t == nt - 2);
;             const char* a1 = cA + (size_t)(t + 1) * kstep;
;             const char* a2 = last ? nA : cA + (size_t)(t + 2) * kstep; const char* b2 = last ? nB : cB + (size_t)(t + 2) * kstep;
;             const char* a3 = a2 + kstep; const char* b3 = b2 + kstep;
;     ...
;             PG8_WAIT_V(8); PG8_WAIT_L(0); PG8_BAR; PG8_MMA(0, 0, At, B0); PG8_MMA(0, 1, At, B1); PG8_BAR; PG8_SCHED;
;             PG8_LDA(At, 1, 1); PG8_STAGE(PG8_SB(1, 0), b3, voffB); PG8_STAGE(PG8_SB(1, 1), b3 + hstep, voffB); PG8_STAGE(PG8_SA(1, 0), a3, voffA);
;             PG8_WAIT_V(8); PG8_WAIT_L(0); PG8_BAR; PG8_MMA(1, 0, At, B0); PG8_MMA(1, 1, At, B1); PG8_BAR; PG8_SCHED;
	s_add_i32 s55, s55, s10
	v_lshl_add_u64 v[234:235], v[234:235], 0, s[34:35]
	s_mov_b32 m0, s55
	ds_read_b128 v[180:183], v217 offset:49152
	ds_read_b128 v[184:187], v217 offset:50176
	ds_read_b128 v[188:191], v217 offset:51200
	ds_read_b128 v[192:195], v217 offset:52224
	ds_read_b128 v[218:221], v217 offset:53248
	ds_read_b128 v[222:225], v217 offset:54272
	ds_read_b128 v[226:229], v217 offset:55296
	ds_read_b128 v[230:233], v217 offset:56320
	global_load_lds_dwordx4 v[234:235], off
	s_add_i32 m0, s55, 0x2000
	s_add_u32 s56, s74, 0x40080
	v_lshl_add_u64 v[234:235], v[236:237], 0, s[34:35]
	s_addc_u32 s57, s75, 0
	s_add_i32 s55, s58, s10
	global_load_lds_dwordx4 v[234:235], off
	v_lshl_add_u64 v[234:235], s[56:57], 0, v[156:157]
	s_mov_b32 m0, s55
	s_nop 0
	global_load_lds_dwordx4 v[234:235], off
	v_lshl_add_u64 v[234:235], s[56:57], 0, v[168:169]
	s_add_i32 m0, s55, 0x2000
	s_nop 0
	global_load_lds_dwordx4 v[234:235], off
	v_lshl_add_u64 v[234:235], v[238:239], 0, s[34:35]
	s_mov_b32 m0, s15
	s_nop 0
	global_load_lds_dwordx4 v[234:235], off
	v_lshl_add_u64 v[234:235], v[240:241], 0, s[34:35]
	s_mov_b32 m0, s16
	s_nop 0
	global_load_lds_dwordx4 v[234:235], off
	s_waitcnt vmcnt(8)
	s_waitcnt lgkmcnt(0)
	s_barrier
	s_setprio 1
	s_waitcnt lgkmcnt(0)
	v_mfma_f32_16x16x32_bf16 v[64:67], v[56:59], v[180:183], v[64:67]
	v_mfma_f32_16x16x32_bf16 v[60:63], v[96:99], v[180:183], v[60:63]
	v_mfma_f32_16x16x32_bf16 v[44:47], v[56:59], v[188:191], v[44:47]
	v_mfma_f32_16x16x32_bf16 v[40:43], v[96:99], v[188:191], v[40:43]
	v_mfma_f32_16x16x32_bf16 v[28:31], v[56:59], v[218:221], v[28:31]
	v_mfma_f32_16x16x32_bf16 v[24:27], v[96:99], v[218:221], v[24:27]
	v_mfma_f32_16x16x32_bf16 v[12:15], v[56:59], v[226:229], v[12:15]
	v_mfma_f32_16x16x32_bf16 v[8:11], v[96:99], v[226:229], v[8:11]
	v_mfma_f32_16x16x32_bf16 v[64:67], v[76:79], v[184:187], v[64:67]
	v_mfma_f32_16x16x32_bf16 v[60:63], v[116:119], v[184:187], v[60:63]
	v_mfma_f32_16x16x32_bf16 v[44:47], v[76:79], v[192:195], v[44:47]
	v_mfma_f32_16x16x32_bf16 v[40:43], v[116:119], v[192:195], v[40:43]
	v_mfma_f32_16x16x32_bf16 v[28:31], v[76:79], v[222:225], v[28:31]
	v_mfma_f32_16x16x32_bf16 v[24:27], v[116:119], v[222:225], v[24:27]
	v_mfma_f32_16x16x32_bf16 v[12:15], v[76:79], v[230:233], v[12:15]
	v_mfma_f32_16x16x32_bf16 v[8:11], v[116:119], v[230:233], v[8:11]
	s_setprio 0
	s_setprio 1
	v_mfma_f32_16x16x32_bf16 v[52:55], v[136:139], v[180:183], v[52:55]
	v_mfma_f32_16x16x32_bf16 v[48:51], v[152:155], v[180:183], v[48:51]
	v_mfma_f32_16x16x32_bf16 v[36:39], v[136:139], v[188:191], v[36:39]
	v_mfma_f32_16x16x32_bf16 v[32:35], v[152:155], v[188:191], v[32:35]
	v_mfma_f32_16x16x32_bf16 v[20:23], v[136:139], v[218:221], v[20:23]
	v_mfma_f32_16x16x32_bf16 v[16:19], v[152:155], v[218:221], v[16:19]
	v_mfma_f32_16x16x32_bf16 v[4:7], v[136:139], v[226:229], v[4:7]
	v_mfma_f32_16x16x32_bf16 v[0:3], v[152:155], v[226:229], v[0:3]
	v_mfma_f32_16x16x32_bf16 v[52:55], v[148:151], v[184:187], v[52:55]
	v_mfma_f32_16x16x32_bf16 v[48:51], v[176:179], v[184:187], v[48:51]
	v_mfma_f32_16x16x32_bf16 v[36:39], v[148:151], v[192:195], v[36:39]
	v_mfma_f32_16x16x32_bf16 v[32:35], v[176:179], v[192:195], v[32:35]
	v_mfma_f32_16x16x32_bf16 v[20:23], v[148:151], v[222:225], v[20:23]
	v_mfma_f32_16x16x32_bf16 v[16:19], v[176:179], v[222:225], v[16:19]
	v_mfma_f32_16x16x32_bf16 v[4:7], v[148:151], v[230:233], v[4:7]
	v_mfma_f32_16x16x32_bf16 v[0:3], v[176:179], v[230:233], v[0:3]
	s_setprio 0
	s_add_i32 s54, s54, 2
	s_add_u32 s44, s44, 0x100
	s_addc_u32 s45, s45, 0
	s_add_u32 s48, s48, 0x100
	s_addc_u32 s49, s49, 0
	s_add_u32 s55, s44, 0xfffc0080
	s_addc_u32 s56, s45, -1
	s_add_i32 s57, 0, 0x10000
	s_cmp_eq_u32 s54, 12
	s_cselect_b32 s77, s8, s56
	s_cselect_b32 s76, s27, s55
	s_cselect_b32 s75, s25, s49
	s_cselect_b32 s74, s39, s48
	s_add_i32 s55, 0, 0x14000
	v_add_u32_e32 v116, s57, v215
	v_add_u32_e32 v176, s55, v215
	s_cmp_gt_u32 s54, 13
	s_barrier
	s_cbranch_scc0 .Lks_head
	s_and_b64 vcc, exec, s[20:21]
	s_cbranch_vccz .LBB0_470
	s_barrier
